# P4 mix epilogue: first-row-group gate loads of each block through a ds_bpermute'd address, results un-permuted after the block's first wait, on top of v025
# speedup vs baseline: 1.0153x; 1.0153x over previous
;     DEVI void init() { G = gridDim.x; const int b = blockIdx.x; if ((G & 7) == 0) { x = b & 7; j = b >> 3; nloc = G >> 3; } else { x = -1; j = b; nloc = G; } }
;     DEVI void init(bool pr) { pair = pr; G = gridDim.x; const int b = blockIdx.x; if ((G & 7) == 0) { x = b & 7; j = b >> 3; nloc = G >> 3; } else { x = -1; j = b; nloc = G; } }
; template <class Epi, class Sched>
; __device__ __forceinline__ void gemm_phase(PG8_LAS unsigned char* lds, const Gemm g, const Sched& S, const Epi& E) {
;     int tid = threadIdx.x; asm volatile("" : "+v"(tid));
;     const int wid = __builtin_amdgcn_readfirstlane(tid >> 6), lane = tid & 63, wr = wid >> 2, wc = wid & 3, fr = lane & 15, fq = lane >> 4;
; template <int PH>
; DEVI void run_phase(const Params& p, unsigned char* smem) {
;     ...
;     } else if (PH == 4) {
;         for (int t = bid; t < 256; t += nb) mini_mix_tile(p, t);
;         EpiMix epi; epi.pp = &p;
;         const bf16_t* OA = (const bf16_t*)(p.ws + W_OAB); const bf16_t* WAT = (const bf16_t*)(p.ws + W_WABT);
;         pg8::Gemm g{OA, WAT, OA + (size_t)NTOK * 512, WAT + 1024 * 512, 512};
;         OrderP4 S; S.init(true);
;         pg8::gemm_phase(lds, g, S, epi);
.LBB0_999:
	v_and_b32_e32 v252, 63, v203
	v_and_b32_e32 v253, 3, v252
	v_lshrrev_b32_e32 v254, 4, v252
	v_bfe_u32 v255, v252, 2, 2
	v_lshl_add_u32 v250, v254, 2, v255
	v_lshl_add_u32 v250, v253, 4, v250
	v_lshlrev_b32_e32 v250, 2, v250
	v_lshlrev_b32_e32 v251, 4, v255
	v_lshl_add_u32 v251, v253, 2, v251
	v_add_u32_e32 v251, v251, v254
	v_lshlrev_b32_e32 v251, 2, v251
	v_and_b32_e32 v238, 63, v203
	v_and_b32_e32 v239, 3, v238
	v_lshrrev_b32_e32 v237, 4, v238
	v_bfe_u32 v236, v238, 2, 2
	v_lshl_add_u32 v237, v237, 2, v236
	v_and_b32_e32 v236, 1, v239
	v_lshrrev_b32_e32 v239, 1, v239
	v_lshl_or_b32 v239, v236, 1, v239
	v_lshl_add_u32 v239, v239, 4, v237
	v_lshlrev_b32_e32 v239, 2, v239
	v_mov_b32_e32 v8, v203
	s_and_b64 vcc, exec, s[78:79]
	v_readfirstlane_b32 s10, v8
	s_cbranch_vccz .LBB0_1163
	s_cmpk_lt_i32 s91, 0x200
	s_cselect_b64 s[0:1], -1, 0
	s_mov_b32 s2, s74
	s_cbranch_execnz .LBB0_1002

;     DEVI void operator()(const f32x4 (&acc)[2][2][4][2], const pg8::Unit& u, int wr, int wc, int l15, int g) const {
;     ...
;             u32x2 gq[4][2][2], pv[4][2][2];
; #pragma unroll
;             for (int m = 2 * mh; m < 2 * mh + 2; ++m) {
;                 const int tok = u.pm * 256 + 128 * ai + 64 * wr + 16 * m + l15;
; #pragma unroll
;                 for (int bj = 0; bj < 2; ++bj)
; #pragma unroll
;                     for (int n = 0; n < 2; ++n) {
;                         const int col = colb + 128 * bj + 16 * n;
;                         gq[m][bj][n] = *(const u32x2*)(G + (size_t)tok * 2048 + (u.w ? 1024 : 0) + col);
;                         if (u.w) pv[m][bj][n] = *(const u32x2*)(MX + (size_t)tok * 1024 + col);
;                     }
.LBB0_1019:
	s_lshl_b32 s24, s24, 8
	s_lshl_b32 s15, s4, 8
	s_cmp_lg_u32 s5, 0
	s_cselect_b64 s[28:29], -1, 0
	s_cmp_eq_u32 s5, 0
	s_cselect_b64 s[4:5], -1, 0
	v_readlane_b32 s52, v234, 24
	s_and_b64 vcc, s[4:5], exec
	v_readlane_b32 s66, v234, 38
	v_readlane_b32 s67, v234, 39
	v_add_u32_e32 v140, s15, v180
	s_cselect_b32 s3, 0, 0x800
	s_mov_b64 s[26:27], s[66:67]
	s_add_u32 s26, s26, s3
	v_ashrrev_i32_e32 v141, 31, v140
	v_or_b32_e32 v142, s24, v182
	s_addc_u32 s27, s27, 0
	v_lshlrev_b64 v[144:145], 12, v[140:141]
	v_lshl_add_u64 v[144:145], s[26:27], 0, v[144:145]
	v_ashrrev_i32_e32 v143, 31, v142
	v_lshl_add_u64 v[146:147], v[142:143], 1, v[144:145]
	ds_bpermute_b32 v248, v250, v146
	ds_bpermute_b32 v249, v250, v147
	s_waitcnt lgkmcnt(0)
	global_load_dwordx2 v[176:177], v[248:249], off
	v_lshlrev_b64 v[172:173], 11, v[140:141]
	v_lshl_add_u64 v[144:145], s[88:89], 0, v[172:173]
	v_lshl_add_u64 v[144:145], v[142:143], 1, v[144:145]
	v_readlane_b32 s53, v234, 25
	v_readlane_b32 s54, v234, 26
	v_readlane_b32 s55, v234, 27
	v_readlane_b32 s56, v234, 28
	v_readlane_b32 s57, v234, 29
	v_readlane_b32 s58, v234, 30
	v_readlane_b32 s59, v234, 31
	v_readlane_b32 s60, v234, 32
	v_readlane_b32 s61, v234, 33
	v_readlane_b32 s62, v234, 34
	v_readlane_b32 s63, v234, 35
	v_readlane_b32 s64, v234, 36
	v_readlane_b32 s65, v234, 37
	s_cbranch_vccnz .LBB0_1021
	global_load_dwordx2 v[158:159], v[144:145], off
.LBB0_1021:
	global_load_dwordx2 v[174:175], v[248:249], off offset:32
	v_cndmask_b32_e64 v139, 0, 1, s[28:29]
	v_cmp_ne_u32_e64 s[4:5], 1, v139
	s_andn2_b64 vcc, exec, s[28:29]
	s_cbranch_vccnz .LBB0_1029
	global_load_dwordx2 v[156:157], v[144:145], off offset:32
	global_load_dwordx2 v[170:171], v[248:249], off offset:256
	s_and_b64 vcc, exec, s[4:5]
	s_cbranch_vccz .LBB0_1030
.LBB0_1023:
	global_load_dwordx2 v[168:169], v[248:249], off offset:288
	s_and_b64 vcc, exec, s[4:5]
	s_cbranch_vccnz .LBB0_1025

;     DEVI void operator()(const f32x4 (&acc)[2][2][4][2], const pg8::Unit& u, int wr, int wc, int l15, int g) const {
;     ...
;                 for (int bj = 0; bj < 2; ++bj)
; #pragma unroll
;                     for (int n = 0; n < 2; ++n) {
;                         const int col = colb + 128 * bj + 16 * n;
;                         gq[m][bj][n] = *(const u32x2*)(G + (size_t)tok * 2048 + (u.w ? 1024 : 0) + col);
;                         if (u.w) pv[m][bj][n] = *(const u32x2*)(MX + (size_t)tok * 1024 + col);
;                     }
.LBB0_1029:
	global_load_dwordx2 v[170:171], v[248:249], off offset:256
	s_and_b64 vcc, exec, s[4:5]
	s_cbranch_vccnz .LBB0_1023
.LBB0_1030:
	global_load_dwordx2 v[154:155], v[144:145], off offset:256
	global_load_dwordx2 v[168:169], v[248:249], off offset:288
	s_and_b64 vcc, exec, s[4:5]
	s_cbranch_vccz .LBB0_1024
	s_branch .LBB0_1025

; DEVI unsigned pk_bf16(float lo, float hi) { const f32x2_t v = {lo, hi}; const bf16x2_t b = __builtin_convertvector(v, bf16x2_t); return __builtin_bit_cast(unsigned, b); }
; DEVI float bf_lo(unsigned u) { return __uint_as_float(u << 16); }
; DEVI float bf_hi(unsigned u) { return __uint_as_float(u & 0xffff0000u); }
;     DEVI void operator()(const f32x4 (&acc)[2][2][4][2], const pg8::Unit& u, int wr, int wc, int l15, int g) const {
;     ...
;             for (int m = 2 * mh; m < 2 * mh + 2; ++m) {
;                 const int tok = u.pm * 256 + 128 * ai + 64 * wr + 16 * m + l15;
; #pragma unroll
;                 for (int bj = 0; bj < 2; ++bj) {
;                     unsigned pk[2][2];
; #pragma unroll
;                     for (int n = 0; n < 2; ++n) {
;                         const f32x4 a = acc[ai][bj][m][n];
;                         const u32x2 gg = gq[m][bj][n];
;                         f32x4 t;
;                         t[0] = a[0] * bf_lo(gg.x); t[1] = a[1] * bf_hi(gg.x); t[2] = a[2] * bf_lo(gg.y); t[3] = a[3] * bf_hi(gg.y);
;                         if (u.w) { const u32x2 q = pv[m][bj][n]; t[0] += bf_lo(q.x); t[1] += bf_hi(q.x); t[2] += bf_lo(q.y); t[3] += bf_hi(q.y); }
;                         pk[n][0] = pk_bf16(t[0], t[1]); pk[n][1] = pk_bf16(t[2], t[3]);
.LBB0_1035:
	s_waitcnt vmcnt(0)
	ds_bpermute_b32 v168, v251, v168
	ds_bpermute_b32 v169, v251, v169
	ds_bpermute_b32 v170, v251, v170
	ds_bpermute_b32 v171, v251, v171
	ds_bpermute_b32 v174, v251, v174
	ds_bpermute_b32 v175, v251, v175
	ds_bpermute_b32 v176, v251, v176
	ds_bpermute_b32 v177, v251, v177
	s_waitcnt lgkmcnt(0)
	v_lshlrev_b32_e32 v178, 16, v176
	v_and_b32_e32 v179, 0xffff0000, v176
	v_lshlrev_b32_e32 v176, 16, v177
	v_and_b32_e32 v177, 0xffff0000, v177
	v_pk_mul_f32 v[124:125], v[124:125], v[178:179]
	s_and_b64 vcc, exec, s[4:5]
	v_pk_mul_f32 v[126:127], v[126:127], v[176:177]
	s_cbranch_vccnz .LBB0_1037
	v_lshlrev_b32_e32 v176, 16, v158
	v_and_b32_e32 v177, 0xffff0000, v158
	v_pk_add_f32 v[124:125], v[124:125], v[176:177]
	v_lshlrev_b32_e32 v176, 16, v159
	v_and_b32_e32 v177, 0xffff0000, v159
	v_pk_add_f32 v[126:127], v[126:127], v[176:177]

;     DEVI void operator()(const f32x4 (&acc)[2][2][4][2], const pg8::Unit& u, int wr, int wc, int l15, int g) const {
;     ...
;             u32x2 gq[4][2][2], pv[4][2][2];
; #pragma unroll
;             for (int m = 2 * mh; m < 2 * mh + 2; ++m) {
;                 const int tok = u.pm * 256 + 128 * ai + 64 * wr + 16 * m + l15;
; #pragma unroll
;                 for (int bj = 0; bj < 2; ++bj)
; #pragma unroll
;                     for (int n = 0; n < 2; ++n) {
;                         const int col = colb + 128 * bj + 16 * n;
;                         gq[m][bj][n] = *(const u32x2*)(G + (size_t)tok * 2048 + (u.w ? 1024 : 0) + col);
;                         if (u.w) pv[m][bj][n] = *(const u32x2*)(MX + (size_t)tok * 1024 + col);
;                     }
;     ...
;                     const auto r0 = __builtin_amdgcn_permlane16_swap(pk[0][0], pk[1][0], false, false);
;                     const auto r1 = __builtin_amdgcn_permlane16_swap(pk[0][1], pk[1][1], false, false);
;                     const u32x4 o = (u32x4){r0[0], r1[0], r0[1], r1[1]};
;                     *(u32x4*)(MX + (size_t)tok * 1024 + u.pn * 256 + 32 * wc + 128 * bj + 16 * (g & 1) + 8 * (g >> 1)) = o;
.LBB0_1051:
	v_cvt_pk_bf16_f32 v100, v100, v101
	v_cvt_pk_bf16_f32 v101, v102, v103
	v_cvt_pk_bf16_f32 v102, v96, v97
	v_or_b32_e32 v96, 32, v140
	v_ashrrev_i32_e32 v97, 31, v96
	v_cvt_pk_bf16_f32 v103, v98, v99
	v_lshlrev_b64 v[98:99], 12, v[96:97]
	v_permlane16_swap_b32_e32 v100, v102
	v_permlane16_swap_b32_e32 v101, v103
	v_lshl_add_u64 v[98:99], s[26:27], 0, v[98:99]
	ds_bpermute_b32 v236, v239, v104
	ds_bpermute_b32 v237, v239, v105
	ds_bpermute_b32 v244, v239, v100
	ds_bpermute_b32 v245, v239, v101
	ds_bpermute_b32 v246, v239, v102
	ds_bpermute_b32 v247, v239, v103
	s_waitcnt lgkmcnt(0)
	global_store_dwordx4 v[236:237], v[244:247], off offset:256
	v_lshl_add_u64 v[98:99], v[142:143], 1, v[98:99]
	ds_bpermute_b32 v248, v250, v98
	ds_bpermute_b32 v249, v250, v99
	s_waitcnt lgkmcnt(0)
	global_load_dwordx2 v[126:127], v[248:249], off
	v_lshlrev_b64 v[96:97], 11, v[96:97]
	v_lshl_add_u64 v[96:97], s[88:89], 0, v[96:97]
	s_and_b64 vcc, exec, s[4:5]
	v_lshl_add_u64 v[96:97], v[142:143], 1, v[96:97]
	s_cbranch_vccnz .LBB0_1055
	global_load_dwordx2 v[110:111], v[96:97], off
	global_load_dwordx2 v[124:125], v[248:249], off offset:32
	s_and_b64 vcc, exec, s[4:5]
	s_cbranch_vccz .LBB0_1056
.LBB0_1053:
	global_load_dwordx2 v[122:123], v[248:249], off offset:256
	s_and_b64 vcc, exec, s[4:5]
	s_cbranch_vccnz .LBB0_1057
.LBB0_1054:
	global_load_dwordx2 v[106:107], v[96:97], off offset:256
	global_load_dwordx2 v[120:121], v[248:249], off offset:288
	s_and_b64 vcc, exec, s[4:5]
	s_cbranch_vccz .LBB0_1058
	s_branch .LBB0_1059
.LBB0_1055:
	global_load_dwordx2 v[124:125], v[248:249], off offset:32
	s_and_b64 vcc, exec, s[4:5]
	s_cbranch_vccnz .LBB0_1053
.LBB0_1056:
	global_load_dwordx2 v[108:109], v[96:97], off offset:32
	global_load_dwordx2 v[122:123], v[248:249], off offset:256
	s_and_b64 vcc, exec, s[4:5]
	s_cbranch_vccz .LBB0_1054
.LBB0_1057:
	global_load_dwordx2 v[120:121], v[248:249], off offset:288
	s_and_b64 vcc, exec, s[4:5]
	s_cbranch_vccnz .LBB0_1059

; DEVI unsigned pk_bf16(float lo, float hi) { const f32x2_t v = {lo, hi}; const bf16x2_t b = __builtin_convertvector(v, bf16x2_t); return __builtin_bit_cast(unsigned, b); }
; DEVI float bf_lo(unsigned u) { return __uint_as_float(u << 16); }
; DEVI float bf_hi(unsigned u) { return __uint_as_float(u & 0xffff0000u); }
;     DEVI void operator()(const f32x4 (&acc)[2][2][4][2], const pg8::Unit& u, int wr, int wc, int l15, int g) const {
;     ...
;             for (int m = 2 * mh; m < 2 * mh + 2; ++m) {
;                 const int tok = u.pm * 256 + 128 * ai + 64 * wr + 16 * m + l15;
; #pragma unroll
;                 for (int bj = 0; bj < 2; ++bj) {
;                     unsigned pk[2][2];
; #pragma unroll
;                     for (int n = 0; n < 2; ++n) {
;                         const f32x4 a = acc[ai][bj][m][n];
;                         const u32x2 gg = gq[m][bj][n];
;                         f32x4 t;
;                         t[0] = a[0] * bf_lo(gg.x); t[1] = a[1] * bf_hi(gg.x); t[2] = a[2] * bf_lo(gg.y); t[3] = a[3] * bf_hi(gg.y);
;                         if (u.w) { const u32x2 q = pv[m][bj][n]; t[0] += bf_lo(q.x); t[1] += bf_hi(q.x); t[2] += bf_lo(q.y); t[3] += bf_hi(q.y); }
;                         pk[n][0] = pk_bf16(t[0], t[1]); pk[n][1] = pk_bf16(t[2], t[3]);
.LBB0_1067:
	s_waitcnt vmcnt(0)
	ds_bpermute_b32 v120, v251, v120
	ds_bpermute_b32 v121, v251, v121
	ds_bpermute_b32 v122, v251, v122
	ds_bpermute_b32 v123, v251, v123
	ds_bpermute_b32 v124, v251, v124
	ds_bpermute_b32 v125, v251, v125
	ds_bpermute_b32 v126, v251, v126
	ds_bpermute_b32 v127, v251, v127
	s_waitcnt lgkmcnt(0)
	v_lshlrev_b32_e32 v160, 16, v126
	v_and_b32_e32 v161, 0xffff0000, v126
	v_lshlrev_b32_e32 v126, 16, v127
	v_and_b32_e32 v127, 0xffff0000, v127
	v_pk_mul_f32 v[92:93], v[92:93], v[160:161]
	s_and_b64 vcc, exec, s[4:5]
	v_pk_mul_f32 v[94:95], v[94:95], v[126:127]
	s_cbranch_vccnz .LBB0_1069
	v_lshlrev_b32_e32 v126, 16, v110
	v_and_b32_e32 v127, 0xffff0000, v110
	v_pk_add_f32 v[92:93], v[92:93], v[126:127]
	v_lshlrev_b32_e32 v126, 16, v111
	v_and_b32_e32 v127, 0xffff0000, v111
	v_pk_add_f32 v[94:95], v[94:95], v[126:127]

;     DEVI void operator()(const f32x4 (&acc)[2][2][4][2], const pg8::Unit& u, int wr, int wc, int l15, int g) const {
;     ...
;             u32x2 gq[4][2][2], pv[4][2][2];
; #pragma unroll
;             for (int m = 2 * mh; m < 2 * mh + 2; ++m) {
;                 const int tok = u.pm * 256 + 128 * ai + 64 * wr + 16 * m + l15;
; #pragma unroll
;                 for (int bj = 0; bj < 2; ++bj)
; #pragma unroll
;                     for (int n = 0; n < 2; ++n) {
;                         const int col = colb + 128 * bj + 16 * n;
;                         gq[m][bj][n] = *(const u32x2*)(G + (size_t)tok * 2048 + (u.w ? 1024 : 0) + col);
;                         if (u.w) pv[m][bj][n] = *(const u32x2*)(MX + (size_t)tok * 1024 + col);
;                     }
;     ...
;                     const auto r0 = __builtin_amdgcn_permlane16_swap(pk[0][0], pk[1][0], false, false);
;                     const auto r1 = __builtin_amdgcn_permlane16_swap(pk[0][1], pk[1][1], false, false);
;                     const u32x4 o = (u32x4){r0[0], r1[0], r0[1], r1[1]};
;                     *(u32x4*)(MX + (size_t)tok * 1024 + u.pn * 256 + 32 * wc + 128 * bj + 16 * (g & 1) + 8 * (g >> 1)) = o;
.LBB0_1083:
	v_cvt_pk_bf16_f32 v68, v68, v69
	v_cvt_pk_bf16_f32 v69, v70, v71
	v_cvt_pk_bf16_f32 v70, v64, v65
	v_add_u32_e32 v64, 0x80, v140
	v_ashrrev_i32_e32 v65, 31, v64
	v_cvt_pk_bf16_f32 v71, v66, v67
	v_lshlrev_b64 v[66:67], 12, v[64:65]
	v_permlane16_swap_b32_e32 v68, v70
	v_permlane16_swap_b32_e32 v69, v71
	v_lshl_add_u64 v[66:67], s[26:27], 0, v[66:67]
	ds_bpermute_b32 v236, v239, v72
	ds_bpermute_b32 v237, v239, v73
	ds_bpermute_b32 v244, v239, v68
	ds_bpermute_b32 v245, v239, v69
	ds_bpermute_b32 v246, v239, v70
	ds_bpermute_b32 v247, v239, v71
	s_waitcnt lgkmcnt(0)
	global_store_dwordx4 v[236:237], v[244:247], off offset:256
	v_lshlrev_b64 v[78:79], 11, v[64:65]
	s_and_b64 vcc, exec, s[4:5]
	v_lshl_add_u64 v[68:69], v[142:143], 1, v[66:67]
	ds_bpermute_b32 v248, v250, v68
	ds_bpermute_b32 v249, v250, v69
	s_waitcnt lgkmcnt(0)
	global_load_dwordx2 v[82:83], v[248:249], off
	v_lshl_add_u64 v[66:67], s[88:89], 0, v[78:79]
	v_lshl_add_u64 v[66:67], v[142:143], 1, v[66:67]
	s_cbranch_vccnz .LBB0_1087
	global_load_dwordx2 v[158:159], v[66:67], off
	global_load_dwordx2 v[80:81], v[248:249], off offset:32
	s_and_b64 vcc, exec, s[4:5]
	s_cbranch_vccz .LBB0_1088
.LBB0_1085:
	global_load_dwordx2 v[76:77], v[248:249], off offset:256
	s_and_b64 vcc, exec, s[4:5]
	s_cbranch_vccnz .LBB0_1089
.LBB0_1086:
	global_load_dwordx2 v[154:155], v[66:67], off offset:256
	global_load_dwordx2 v[74:75], v[248:249], off offset:288
	s_and_b64 vcc, exec, s[4:5]
	s_cbranch_vccz .LBB0_1090
	s_branch .LBB0_1091
.LBB0_1087:
	global_load_dwordx2 v[80:81], v[248:249], off offset:32
	s_and_b64 vcc, exec, s[4:5]
	s_cbranch_vccnz .LBB0_1085
.LBB0_1088:
	global_load_dwordx2 v[156:157], v[66:67], off offset:32
	global_load_dwordx2 v[76:77], v[248:249], off offset:256
	s_and_b64 vcc, exec, s[4:5]
	s_cbranch_vccz .LBB0_1086
.LBB0_1089:
	global_load_dwordx2 v[74:75], v[248:249], off offset:288
	s_and_b64 vcc, exec, s[4:5]
	s_cbranch_vccnz .LBB0_1091

; DEVI unsigned pk_bf16(float lo, float hi) { const f32x2_t v = {lo, hi}; const bf16x2_t b = __builtin_convertvector(v, bf16x2_t); return __builtin_bit_cast(unsigned, b); }
; DEVI float bf_lo(unsigned u) { return __uint_as_float(u << 16); }
; DEVI float bf_hi(unsigned u) { return __uint_as_float(u & 0xffff0000u); }
;     DEVI void operator()(const f32x4 (&acc)[2][2][4][2], const pg8::Unit& u, int wr, int wc, int l15, int g) const {
;     ...
;             for (int m = 2 * mh; m < 2 * mh + 2; ++m) {
;                 const int tok = u.pm * 256 + 128 * ai + 64 * wr + 16 * m + l15;
; #pragma unroll
;                 for (int bj = 0; bj < 2; ++bj) {
;                     unsigned pk[2][2];
; #pragma unroll
;                     for (int n = 0; n < 2; ++n) {
;                         const f32x4 a = acc[ai][bj][m][n];
;                         const u32x2 gg = gq[m][bj][n];
;                         f32x4 t;
;                         t[0] = a[0] * bf_lo(gg.x); t[1] = a[1] * bf_hi(gg.x); t[2] = a[2] * bf_lo(gg.y); t[3] = a[3] * bf_hi(gg.y);
;                         if (u.w) { const u32x2 q = pv[m][bj][n]; t[0] += bf_lo(q.x); t[1] += bf_hi(q.x); t[2] += bf_lo(q.y); t[3] += bf_hi(q.y); }
;                         pk[n][0] = pk_bf16(t[0], t[1]); pk[n][1] = pk_bf16(t[2], t[3]);
.LBB0_1099:
	s_waitcnt vmcnt(0)
	ds_bpermute_b32 v74, v251, v74
	ds_bpermute_b32 v75, v251, v75
	ds_bpermute_b32 v76, v251, v76
	ds_bpermute_b32 v77, v251, v77
	ds_bpermute_b32 v80, v251, v80
	ds_bpermute_b32 v81, v251, v81
	ds_bpermute_b32 v82, v251, v82
	ds_bpermute_b32 v83, v251, v83
	s_waitcnt lgkmcnt(0)
	v_lshlrev_b32_e32 v84, 16, v82
	v_and_b32_e32 v85, 0xffff0000, v82
	v_lshlrev_b32_e32 v82, 16, v83
	v_and_b32_e32 v83, 0xffff0000, v83
	v_pk_mul_f32 v[60:61], v[60:61], v[84:85]
	s_and_b64 vcc, exec, s[4:5]
	v_pk_mul_f32 v[62:63], v[62:63], v[82:83]
	s_cbranch_vccnz .LBB0_1101
	v_lshlrev_b32_e32 v82, 16, v158
	v_and_b32_e32 v83, 0xffff0000, v158
	v_pk_add_f32 v[60:61], v[60:61], v[82:83]
	v_lshlrev_b32_e32 v82, 16, v159
	v_and_b32_e32 v83, 0xffff0000, v159
	v_pk_add_f32 v[62:63], v[62:63], v[82:83]

;     DEVI void operator()(const f32x4 (&acc)[2][2][4][2], const pg8::Unit& u, int wr, int wc, int l15, int g) const {
;     ...
;             u32x2 gq[4][2][2], pv[4][2][2];
; #pragma unroll
;             for (int m = 2 * mh; m < 2 * mh + 2; ++m) {
;                 const int tok = u.pm * 256 + 128 * ai + 64 * wr + 16 * m + l15;
; #pragma unroll
;                 for (int bj = 0; bj < 2; ++bj)
; #pragma unroll
;                     for (int n = 0; n < 2; ++n) {
;                         const int col = colb + 128 * bj + 16 * n;
;                         gq[m][bj][n] = *(const u32x2*)(G + (size_t)tok * 2048 + (u.w ? 1024 : 0) + col);
;                         if (u.w) pv[m][bj][n] = *(const u32x2*)(MX + (size_t)tok * 1024 + col);
;                     }
;     ...
;                     const auto r0 = __builtin_amdgcn_permlane16_swap(pk[0][0], pk[1][0], false, false);
;                     const auto r1 = __builtin_amdgcn_permlane16_swap(pk[0][1], pk[1][1], false, false);
;                     const u32x4 o = (u32x4){r0[0], r1[0], r0[1], r1[1]};
;                     *(u32x4*)(MX + (size_t)tok * 1024 + u.pn * 256 + 32 * wc + 128 * bj + 16 * (g & 1) + 8 * (g >> 1)) = o;
.LBB0_1115:
	v_cvt_pk_bf16_f32 v36, v36, v37
	v_cvt_pk_bf16_f32 v37, v38, v39
	v_cvt_pk_bf16_f32 v38, v32, v33
	v_or_b32_e32 v32, 32, v64
	v_ashrrev_i32_e32 v33, 31, v32
	v_cvt_pk_bf16_f32 v39, v34, v35
	v_lshlrev_b64 v[34:35], 12, v[32:33]
	v_permlane16_swap_b32_e32 v36, v38
	v_permlane16_swap_b32_e32 v37, v39
	v_lshl_add_u64 v[34:35], s[26:27], 0, v[34:35]
	ds_bpermute_b32 v236, v239, v40
	ds_bpermute_b32 v237, v239, v41
	ds_bpermute_b32 v244, v239, v36
	ds_bpermute_b32 v245, v239, v37
	ds_bpermute_b32 v246, v239, v38
	ds_bpermute_b32 v247, v239, v39
	s_waitcnt lgkmcnt(0)
	global_store_dwordx4 v[236:237], v[244:247], off offset:256
	v_lshl_add_u64 v[34:35], v[142:143], 1, v[34:35]
	ds_bpermute_b32 v248, v250, v34
	ds_bpermute_b32 v249, v250, v35
	s_waitcnt lgkmcnt(0)
	global_load_dwordx2 v[46:47], v[248:249], off
	v_lshlrev_b64 v[32:33], 11, v[32:33]
	v_lshl_add_u64 v[32:33], s[88:89], 0, v[32:33]
	s_and_b64 vcc, exec, s[4:5]
	v_lshl_add_u64 v[32:33], v[142:143], 1, v[32:33]
	s_cbranch_vccnz .LBB0_1119
	global_load_dwordx2 v[110:111], v[32:33], off
	global_load_dwordx2 v[44:45], v[248:249], off offset:32
	s_and_b64 vcc, exec, s[4:5]
	s_cbranch_vccz .LBB0_1120
.LBB0_1117:
	global_load_dwordx2 v[42:43], v[248:249], off offset:256
	s_and_b64 vcc, exec, s[4:5]
	s_cbranch_vccnz .LBB0_1121
.LBB0_1118:
	global_load_dwordx2 v[106:107], v[32:33], off offset:256
	global_load_dwordx2 v[40:41], v[248:249], off offset:288
	s_and_b64 vcc, exec, s[4:5]
	s_cbranch_vccz .LBB0_1122
	s_branch .LBB0_1123
.LBB0_1119:
	global_load_dwordx2 v[44:45], v[248:249], off offset:32
	s_and_b64 vcc, exec, s[4:5]
	s_cbranch_vccnz .LBB0_1117
.LBB0_1120:
	global_load_dwordx2 v[108:109], v[32:33], off offset:32
	global_load_dwordx2 v[42:43], v[248:249], off offset:256
	s_and_b64 vcc, exec, s[4:5]
	s_cbranch_vccz .LBB0_1118
.LBB0_1121:
	global_load_dwordx2 v[40:41], v[248:249], off offset:288
	s_and_b64 vcc, exec, s[4:5]
	s_cbranch_vccnz .LBB0_1123

; DEVI unsigned pk_bf16(float lo, float hi) { const f32x2_t v = {lo, hi}; const bf16x2_t b = __builtin_convertvector(v, bf16x2_t); return __builtin_bit_cast(unsigned, b); }
; DEVI float bf_lo(unsigned u) { return __uint_as_float(u << 16); }
; DEVI float bf_hi(unsigned u) { return __uint_as_float(u & 0xffff0000u); }
;     DEVI void operator()(const f32x4 (&acc)[2][2][4][2], const pg8::Unit& u, int wr, int wc, int l15, int g) const {
;     ...
;             for (int m = 2 * mh; m < 2 * mh + 2; ++m) {
;                 const int tok = u.pm * 256 + 128 * ai + 64 * wr + 16 * m + l15;
; #pragma unroll
;                 for (int bj = 0; bj < 2; ++bj) {
;                     unsigned pk[2][2];
; #pragma unroll
;                     for (int n = 0; n < 2; ++n) {
;                         const f32x4 a = acc[ai][bj][m][n];
;                         const u32x2 gg = gq[m][bj][n];
;                         f32x4 t;
;                         t[0] = a[0] * bf_lo(gg.x); t[1] = a[1] * bf_hi(gg.x); t[2] = a[2] * bf_lo(gg.y); t[3] = a[3] * bf_hi(gg.y);
;                         if (u.w) { const u32x2 q = pv[m][bj][n]; t[0] += bf_lo(q.x); t[1] += bf_hi(q.x); t[2] += bf_lo(q.y); t[3] += bf_hi(q.y); }
;                         pk[n][0] = pk_bf16(t[0], t[1]); pk[n][1] = pk_bf16(t[2], t[3]);
.LBB0_1131:
	s_waitcnt vmcnt(0)
	ds_bpermute_b32 v40, v251, v40
	ds_bpermute_b32 v41, v251, v41
	ds_bpermute_b32 v42, v251, v42
	ds_bpermute_b32 v43, v251, v43
	ds_bpermute_b32 v44, v251, v44
	ds_bpermute_b32 v45, v251, v45
	ds_bpermute_b32 v46, v251, v46
	ds_bpermute_b32 v47, v251, v47
	s_waitcnt lgkmcnt(0)
	v_lshlrev_b32_e32 v48, 16, v46
	v_and_b32_e32 v49, 0xffff0000, v46
	v_lshlrev_b32_e32 v46, 16, v47
	v_and_b32_e32 v47, 0xffff0000, v47
	v_pk_mul_f32 v[28:29], v[28:29], v[48:49]
	s_and_b64 vcc, exec, s[4:5]
	v_pk_mul_f32 v[30:31], v[30:31], v[46:47]
	s_cbranch_vccnz .LBB0_1133
	v_lshlrev_b32_e32 v46, 16, v110
	v_and_b32_e32 v47, 0xffff0000, v110
	v_pk_add_f32 v[28:29], v[28:29], v[46:47]
	v_lshlrev_b32_e32 v46, 16, v111
	v_and_b32_e32 v47, 0xffff0000, v111
	v_pk_add_f32 v[30:31], v[30:31], v[46:47]
